# tighter schedule of hand-written interior steps (V reads fill permlane slots, single PV wait)
# speedup vs baseline: 1.0412x; 1.0063x over previous
; template <int CGM>
; __device__ __forceinline__ void step_int(const bf16x8 (&kf)[4][2], const bf16x8 (&q)[2][2], float farb, const bool (&selq)[2],
;                                          float (&m)[2], float (&l)[2], f32x4 (&o)[2][4], const unsigned char* Vs, int r, int fq) {
;     f32x4 s[2][4]; float mx[2] = {-1e30f, -1e30f};
; #pragma unroll
;     for (int cg_ = 0; cg_ < 2; ++cg_) if ((CGM >> cg_) & 1) { qk(s[cg_], kf, q[cg_], selq[cg_] ? farb - m[cg_] : -1e30f); mx[cg_] = red_max4(max16v(s[cg_])); }
;     if (__any(mx[0] > 0.f || mx[1] > 0.f)) {
; #pragma unroll
;         for (int cg_ = 0; cg_ < 2; ++cg_) if ((CGM >> cg_) & 1) {
;             const float d = fmaxf(mx[cg_], 0.f), sc = __builtin_amdgcn_exp2f(-d); m[cg_] += d; l[cg_] *= sc;
; #pragma unroll
;             for (int df = 0; df < 4; ++df) o[cg_][df] *= sc;
; #pragma unroll
;             for (int f = 0; f < 4; ++f) s[cg_][f] -= d;
;         }
;     }
.Lsel_c3:
	v_sub_f32_e32 v128, v18, v124
	v_sub_f32_e32 v144, v18, v125
	v_cndmask_b32_e64 v128, v148, v128, s[10:11]
	v_cndmask_b32_e64 v144, v148, v144, s[8:9]
	v_mov_b32_e32 v129, v128
	v_mov_b32_e32 v145, v144
	v_mov_b64_e32 v[130:131], v[128:129]
	v_mov_b64_e32 v[146:147], v[144:145]
	s_waitcnt lgkmcnt(7)
	v_mfma_f32_16x16x32_bf16 v[92:95], v[88:91], v[2:5], v[128:131]
	v_mfma_f32_16x16x32_bf16 v[108:111], v[88:91], v[10:13], v[144:147]
	s_waitcnt lgkmcnt(6)
	v_mfma_f32_16x16x32_bf16 v[96:99], v[80:83], v[2:5], v[128:131]
	v_mfma_f32_16x16x32_bf16 v[112:115], v[80:83], v[10:13], v[144:147]
	s_waitcnt lgkmcnt(5)
	v_mfma_f32_16x16x32_bf16 v[92:95], v[84:87], v[6:9], v[92:95]
	v_mfma_f32_16x16x32_bf16 v[108:111], v[84:87], v[14:17], v[108:111]
	s_waitcnt lgkmcnt(4)
	v_mfma_f32_16x16x32_bf16 v[96:99], v[76:79], v[6:9], v[96:99]
	v_mfma_f32_16x16x32_bf16 v[112:115], v[76:79], v[14:17], v[112:115]
	s_waitcnt lgkmcnt(3)
	v_mfma_f32_16x16x32_bf16 v[100:103], v[72:75], v[2:5], v[128:131]
	v_mfma_f32_16x16x32_bf16 v[116:119], v[72:75], v[10:13], v[144:147]
	s_waitcnt lgkmcnt(2)
	v_mfma_f32_16x16x32_bf16 v[104:107], v[60:63], v[2:5], v[128:131]
	v_mfma_f32_16x16x32_bf16 v[120:123], v[60:63], v[10:13], v[144:147]
	s_waitcnt lgkmcnt(1)
	v_mfma_f32_16x16x32_bf16 v[100:103], v[68:71], v[6:9], v[100:103]
	v_mfma_f32_16x16x32_bf16 v[116:119], v[68:71], v[14:17], v[116:119]
	s_waitcnt lgkmcnt(0)
	v_mfma_f32_16x16x32_bf16 v[104:107], v[64:67], v[6:9], v[104:107]
	v_mfma_f32_16x16x32_bf16 v[120:123], v[64:67], v[14:17], v[120:123]
	ds_read_b128 v[88:91], v143 offset:8192
	ds_read_b128 v[80:83], v143 offset:8704
	ds_read_b128 v[72:75], v143 offset:12288
	ds_read_b128 v[60:63], v143 offset:12800
	v_max3_f32 v128, v92, v93, v94
	v_max3_f32 v129, v95, v96, v97
	v_max3_f32 v144, v108, v109, v110
	v_max3_f32 v145, v111, v112, v113
	v_max3_f32 v130, v98, v99, v100
	v_max3_f32 v131, v101, v102, v103
	v_max3_f32 v146, v114, v115, v116
	v_max3_f32 v147, v117, v118, v119
	v_max3_f32 v128, v128, v104, v105
	v_max3_f32 v129, v129, v106, v107
	v_max3_f32 v144, v144, v120, v121
	v_max3_f32 v145, v145, v122, v123
	v_max3_f32 v128, v128, v129, v130
	v_max3_f32 v144, v144, v145, v146
	v_max_f32_e32 v128, v128, v131
	v_max_f32_e32 v144, v144, v147
	v_mov_b32_e32 v129, v128
	v_mov_b32_e32 v145, v144
	ds_read_b128 v[84:87], v142 offset:8192
	ds_read_b128 v[76:79], v142 offset:8704
	v_permlane16_swap_b32_e32 v128, v129
	v_permlane16_swap_b32_e32 v144, v145
	v_max_f32_e32 v128, v128, v129
	v_max_f32_e32 v144, v144, v145
	v_mov_b32_e32 v129, v128
	v_mov_b32_e32 v145, v144
	ds_read_b128 v[68:71], v142 offset:12288
	ds_read_b128 v[64:67], v142 offset:12800
	v_permlane32_swap_b32_e32 v128, v129
	v_permlane32_swap_b32_e32 v144, v145
	v_max_f32_e32 v128, v128, v129
	v_max_f32_e32 v144, v144, v145
	v_max_f32_e32 v129, v128, v144
	v_cmp_lt_f32_e32 vcc, 0, v129
	s_cbranch_vccz .Lsel_c3_exp
	v_max_f32_e32 v130, 0, v128
	v_max_f32_e32 v147, 0, v144
	v_exp_f32_e64 v128, -v130
	v_exp_f32_e64 v146, -v147
	v_add_f32_e32 v124, v124, v130
	v_add_f32_e32 v125, v125, v147
	v_sub_f32_e32 v92, v92, v130
	v_sub_f32_e32 v93, v93, v130
	v_sub_f32_e32 v94, v94, v130
	v_sub_f32_e32 v95, v95, v130
	v_sub_f32_e32 v96, v96, v130
	v_sub_f32_e32 v97, v97, v130
	v_sub_f32_e32 v98, v98, v130
	v_sub_f32_e32 v99, v99, v130
	v_sub_f32_e32 v100, v100, v130
	v_sub_f32_e32 v101, v101, v130
	v_sub_f32_e32 v102, v102, v130
	v_sub_f32_e32 v103, v103, v130
	v_sub_f32_e32 v104, v104, v130
	v_sub_f32_e32 v105, v105, v130
	v_sub_f32_e32 v106, v106, v130
	v_sub_f32_e32 v107, v107, v130
	v_sub_f32_e32 v108, v108, v147
	v_sub_f32_e32 v109, v109, v147
	v_sub_f32_e32 v110, v110, v147
	v_sub_f32_e32 v111, v111, v147
	v_sub_f32_e32 v112, v112, v147
	v_sub_f32_e32 v113, v113, v147
	v_sub_f32_e32 v114, v114, v147
	v_sub_f32_e32 v115, v115, v147
	v_sub_f32_e32 v116, v116, v147
	v_sub_f32_e32 v117, v117, v147
	v_sub_f32_e32 v118, v118, v147
	v_sub_f32_e32 v119, v119, v147
	v_sub_f32_e32 v120, v120, v147
	v_sub_f32_e32 v121, v121, v147
	v_sub_f32_e32 v122, v122, v147
	v_sub_f32_e32 v123, v123, v147
	v_mul_f32_e32 v127, v127, v128
	v_pk_mul_f32 v[56:57], v[56:57], v[128:129] op_sel_hi:[1,0]
	v_pk_mul_f32 v[58:59], v[58:59], v[128:129] op_sel_hi:[1,0]
	v_pk_mul_f32 v[52:53], v[52:53], v[128:129] op_sel_hi:[1,0]
	v_pk_mul_f32 v[54:55], v[54:55], v[128:129] op_sel_hi:[1,0]
	v_pk_mul_f32 v[48:49], v[48:49], v[128:129] op_sel_hi:[1,0]
	v_pk_mul_f32 v[50:51], v[50:51], v[128:129] op_sel_hi:[1,0]
	v_pk_mul_f32 v[44:45], v[44:45], v[128:129] op_sel_hi:[1,0]
	v_pk_mul_f32 v[46:47], v[46:47], v[128:129] op_sel_hi:[1,0]
	v_mul_f32_e32 v126, v126, v146
	v_pk_mul_f32 v[40:41], v[40:41], v[146:147] op_sel_hi:[1,0]
	v_pk_mul_f32 v[42:43], v[42:43], v[146:147] op_sel_hi:[1,0]
	v_pk_mul_f32 v[28:29], v[28:29], v[146:147] op_sel_hi:[1,0]
	v_pk_mul_f32 v[30:31], v[30:31], v[146:147] op_sel_hi:[1,0]
	v_pk_mul_f32 v[24:25], v[24:25], v[146:147] op_sel_hi:[1,0]
	v_pk_mul_f32 v[26:27], v[26:27], v[146:147] op_sel_hi:[1,0]
	v_pk_mul_f32 v[20:21], v[20:21], v[146:147] op_sel_hi:[1,0]
	v_pk_mul_f32 v[22:23], v[22:23], v[146:147] op_sel_hi:[1,0]
; template <int CGM>
; __device__ __forceinline__ void pv2(f32x4 (&o)[2][4], const float (&p)[2][4][4], const unsigned char* Vs, int r, int fq) {
;     bf16x8 pb[2][2];
; #pragma unroll
;     for (int cg_ = 0; cg_ < 2; ++cg_) if ((CGM >> cg_) & 1)
; #pragma unroll
;         for (int kc = 0; kc < 2; ++kc) {
;             u32x4 w; w.x = cvt_pk_bf16(p[cg_][2 * kc][0], p[cg_][2 * kc][1]); w.y = cvt_pk_bf16(p[cg_][2 * kc][2], p[cg_][2 * kc][3]);
;             w.z = cvt_pk_bf16(p[cg_][2 * kc + 1][0], p[cg_][2 * kc + 1][1]); w.w = cvt_pk_bf16(p[cg_][2 * kc + 1][2], p[cg_][2 * kc + 1][3]);
;             pb[cg_][kc] = __builtin_bit_cast(bf16x8, w);
;         }
; #pragma unroll
;     for (int df = 0; df < 4; ++df)
; #pragma unroll
;         for (int kc = 0; kc < 2; ++kc) {
;             const int R = prow(df, r);
;             const bf16x8 vf = *(const bf16x8*)(Vs + R * 128 + (((4 * kc + fq) ^ swz(R)) << 4));
;             if (CGM & 1) o[0][df] = __builtin_amdgcn_mfma_f32_16x16x32_bf16(vf, pb[0][kc], o[0][df], 0, 0, 0);
;             if (CGM & 2) o[1][df] = __builtin_amdgcn_mfma_f32_16x16x32_bf16(vf, pb[1][kc], o[1][df], 0, 0, 0);
;         }
; }
; template <int CGM>
; __device__ __forceinline__ void step_int(const bf16x8 (&kf)[4][2], const bf16x8 (&q)[2][2], float farb, const bool (&selq)[2],
;                                          float (&m)[2], float (&l)[2], f32x4 (&o)[2][4], const unsigned char* Vs, int r, int fq) {
;     f32x4 s[2][4]; float mx[2] = {-1e30f, -1e30f};
; #pragma unroll
;     for (int cg_ = 0; cg_ < 2; ++cg_) if ((CGM >> cg_) & 1) { qk(s[cg_], kf, q[cg_], selq[cg_] ? farb - m[cg_] : -1e30f); mx[cg_] = red_max4(max16v(s[cg_])); }
;     if (__any(mx[0] > 0.f || mx[1] > 0.f)) {
; #pragma unroll
;         for (int cg_ = 0; cg_ < 2; ++cg_) if ((CGM >> cg_) & 1) {
;             const float d = fmaxf(mx[cg_], 0.f), sc = __builtin_amdgcn_exp2f(-d); m[cg_] += d; l[cg_] *= sc;
; #pragma unroll
;             for (int df = 0; df < 4; ++df) o[cg_][df] *= sc;
;     ...
;     float p[2][4][4];
; #pragma unroll
;     for (int cg_ = 0; cg_ < 2; ++cg_) if ((CGM >> cg_) & 1) {
;         float rs = 0.f;
; #pragma unroll
;         for (int f = 0; f < 4; ++f)
; #pragma unroll
;             for (int i = 0; i < 4; ++i) { const float pe = __builtin_amdgcn_exp2f(s[cg_][f][i]); p[cg_][f][i] = pe; rs += pe; }
;         l[cg_] += rs;
;     }
;     pv2<CGM>(o, p, Vs, r, fq);
; }
.Lsel_c3_exp:
	v_exp_f32_e32 v92, v92
	v_exp_f32_e32 v93, v93
	v_exp_f32_e32 v94, v94
	v_exp_f32_e32 v95, v95
	v_exp_f32_e32 v96, v96
	v_exp_f32_e32 v97, v97
	v_exp_f32_e32 v98, v98
	v_exp_f32_e32 v99, v99
	v_exp_f32_e32 v100, v100
	v_exp_f32_e32 v101, v101
	v_exp_f32_e32 v102, v102
	v_exp_f32_e32 v103, v103
	v_exp_f32_e32 v104, v104
	v_exp_f32_e32 v105, v105
	v_exp_f32_e32 v106, v106
	v_exp_f32_e32 v107, v107
	v_exp_f32_e32 v108, v108
	v_exp_f32_e32 v109, v109
	v_exp_f32_e32 v110, v110
	v_exp_f32_e32 v111, v111
	v_exp_f32_e32 v112, v112
	v_exp_f32_e32 v113, v113
	v_exp_f32_e32 v114, v114
	v_exp_f32_e32 v115, v115
	v_exp_f32_e32 v116, v116
	v_exp_f32_e32 v117, v117
	v_exp_f32_e32 v118, v118
	v_exp_f32_e32 v119, v119
	v_exp_f32_e32 v120, v120
	v_exp_f32_e32 v121, v121
	v_exp_f32_e32 v122, v122
	v_exp_f32_e32 v123, v123
	v_pk_add_f32 v[130:131], v[92:93], v[94:95]
	v_pk_add_f32 v[130:131], v[130:131], v[96:97]
	v_pk_add_f32 v[130:131], v[130:131], v[98:99]
	v_pk_add_f32 v[130:131], v[130:131], v[100:101]
	v_pk_add_f32 v[130:131], v[130:131], v[102:103]
	v_pk_add_f32 v[130:131], v[130:131], v[104:105]
	v_pk_add_f32 v[130:131], v[130:131], v[106:107]
	v_pk_add_f32 v[146:147], v[108:109], v[110:111]
	v_pk_add_f32 v[146:147], v[146:147], v[112:113]
	v_pk_add_f32 v[146:147], v[146:147], v[114:115]
	v_pk_add_f32 v[146:147], v[146:147], v[116:117]
	v_pk_add_f32 v[146:147], v[146:147], v[118:119]
	v_pk_add_f32 v[146:147], v[146:147], v[120:121]
	v_pk_add_f32 v[146:147], v[146:147], v[122:123]
	v_add_f32_e32 v130, v130, v131
	v_add_f32_e32 v146, v146, v147
	v_add_f32_e32 v127, v127, v130
	v_add_f32_e32 v126, v126, v146
	v_cvt_pk_bf16_f32 v92, v92, v93
	v_cvt_pk_bf16_f32 v93, v94, v95
	v_cvt_pk_bf16_f32 v94, v96, v97
	v_cvt_pk_bf16_f32 v95, v98, v99
	v_cvt_pk_bf16_f32 v96, v100, v101
	v_cvt_pk_bf16_f32 v97, v102, v103
	v_cvt_pk_bf16_f32 v98, v104, v105
	v_cvt_pk_bf16_f32 v99, v106, v107
	v_cvt_pk_bf16_f32 v108, v108, v109
	v_cvt_pk_bf16_f32 v109, v110, v111
	v_cvt_pk_bf16_f32 v110, v112, v113
	v_cvt_pk_bf16_f32 v111, v114, v115
	v_cvt_pk_bf16_f32 v112, v116, v117
	v_cvt_pk_bf16_f32 v113, v118, v119
	v_cvt_pk_bf16_f32 v114, v120, v121
	v_cvt_pk_bf16_f32 v115, v122, v123
	s_waitcnt lgkmcnt(0)
	s_nop 0
	v_mfma_f32_16x16x32_bf16 v[56:59], v[88:91], v[92:95], v[56:59]
	v_mfma_f32_16x16x32_bf16 v[40:43], v[88:91], v[108:111], v[40:43]
	v_mfma_f32_16x16x32_bf16 v[52:55], v[80:83], v[92:95], v[52:55]
	v_mfma_f32_16x16x32_bf16 v[28:31], v[80:83], v[108:111], v[28:31]
	v_mfma_f32_16x16x32_bf16 v[48:51], v[72:75], v[92:95], v[48:51]
	v_mfma_f32_16x16x32_bf16 v[24:27], v[72:75], v[108:111], v[24:27]
	v_mfma_f32_16x16x32_bf16 v[44:47], v[60:63], v[92:95], v[44:47]
	v_mfma_f32_16x16x32_bf16 v[20:23], v[60:63], v[108:111], v[20:23]
	v_mfma_f32_16x16x32_bf16 v[56:59], v[84:87], v[96:99], v[56:59]
	v_mfma_f32_16x16x32_bf16 v[40:43], v[84:87], v[112:115], v[40:43]
	v_mfma_f32_16x16x32_bf16 v[52:55], v[76:79], v[96:99], v[52:55]
	v_mfma_f32_16x16x32_bf16 v[28:31], v[76:79], v[112:115], v[28:31]
	v_mfma_f32_16x16x32_bf16 v[48:51], v[68:71], v[96:99], v[48:51]
	v_mfma_f32_16x16x32_bf16 v[24:27], v[68:71], v[112:115], v[24:27]
	v_mfma_f32_16x16x32_bf16 v[44:47], v[64:67], v[96:99], v[44:47]
	v_mfma_f32_16x16x32_bf16 v[20:23], v[64:67], v[112:115], v[20:23]
	s_branch .LBB0_2481
.Lsel_c1:
	v_sub_f32_e32 v128, v18, v124
	v_cndmask_b32_e64 v128, v148, v128, s[10:11]
	v_mov_b32_e32 v129, v128
	v_mov_b64_e32 v[130:131], v[128:129]
	s_nop 0
	s_waitcnt lgkmcnt(7)
	v_mfma_f32_16x16x32_bf16 v[92:95], v[88:91], v[2:5], v[128:131]
	s_waitcnt lgkmcnt(6)
	v_mfma_f32_16x16x32_bf16 v[96:99], v[80:83], v[2:5], v[128:131]
	s_waitcnt lgkmcnt(5)
	v_mfma_f32_16x16x32_bf16 v[92:95], v[84:87], v[6:9], v[92:95]
	s_waitcnt lgkmcnt(4)
	v_mfma_f32_16x16x32_bf16 v[96:99], v[76:79], v[6:9], v[96:99]
	s_waitcnt lgkmcnt(3)
	v_mfma_f32_16x16x32_bf16 v[100:103], v[72:75], v[2:5], v[128:131]
	s_waitcnt lgkmcnt(2)
	v_mfma_f32_16x16x32_bf16 v[104:107], v[60:63], v[2:5], v[128:131]
	s_waitcnt lgkmcnt(1)
	v_mfma_f32_16x16x32_bf16 v[100:103], v[68:71], v[6:9], v[100:103]
	s_waitcnt lgkmcnt(0)
	v_mfma_f32_16x16x32_bf16 v[104:107], v[64:67], v[6:9], v[104:107]
	ds_read_b128 v[88:91], v143 offset:8192
	ds_read_b128 v[80:83], v143 offset:8704
	ds_read_b128 v[72:75], v143 offset:12288
	ds_read_b128 v[60:63], v143 offset:12800
	v_max3_f32 v128, v92, v93, v94
	v_max3_f32 v129, v95, v96, v97
	v_max3_f32 v130, v98, v99, v100
	v_max3_f32 v131, v101, v102, v103
	v_max3_f32 v128, v128, v104, v105
	v_max3_f32 v129, v129, v106, v107
	v_max3_f32 v128, v128, v129, v130
	v_max_f32_e32 v128, v128, v131
	v_mov_b32_e32 v129, v128
	ds_read_b128 v[84:87], v142 offset:8192
	ds_read_b128 v[76:79], v142 offset:8704
	v_permlane16_swap_b32_e32 v128, v129
	v_max_f32_e32 v128, v128, v129
	v_mov_b32_e32 v129, v128
	ds_read_b128 v[68:71], v142 offset:12288
	ds_read_b128 v[64:67], v142 offset:12800
	v_permlane32_swap_b32_e32 v128, v129
	v_max_f32_e32 v128, v128, v129
	v_cmp_lt_f32_e32 vcc, 0, v128
	s_cbranch_vccz .Lsel_c1_exp
	v_max_f32_e32 v130, 0, v128
	v_exp_f32_e64 v128, -v130
	v_add_f32_e32 v124, v124, v130
	v_sub_f32_e32 v92, v92, v130
	v_sub_f32_e32 v93, v93, v130
	v_sub_f32_e32 v94, v94, v130
	v_sub_f32_e32 v95, v95, v130
	v_sub_f32_e32 v96, v96, v130
	v_sub_f32_e32 v97, v97, v130
	v_sub_f32_e32 v98, v98, v130
	v_sub_f32_e32 v99, v99, v130
	v_sub_f32_e32 v100, v100, v130
	v_sub_f32_e32 v101, v101, v130
	v_sub_f32_e32 v102, v102, v130
	v_sub_f32_e32 v103, v103, v130
	v_sub_f32_e32 v104, v104, v130
	v_sub_f32_e32 v105, v105, v130
	v_sub_f32_e32 v106, v106, v130
	v_sub_f32_e32 v107, v107, v130
	v_mul_f32_e32 v127, v127, v128
	v_pk_mul_f32 v[56:57], v[56:57], v[128:129] op_sel_hi:[1,0]
	v_pk_mul_f32 v[58:59], v[58:59], v[128:129] op_sel_hi:[1,0]
	v_pk_mul_f32 v[52:53], v[52:53], v[128:129] op_sel_hi:[1,0]
	v_pk_mul_f32 v[54:55], v[54:55], v[128:129] op_sel_hi:[1,0]
	v_pk_mul_f32 v[48:49], v[48:49], v[128:129] op_sel_hi:[1,0]
	v_pk_mul_f32 v[50:51], v[50:51], v[128:129] op_sel_hi:[1,0]
	v_pk_mul_f32 v[44:45], v[44:45], v[128:129] op_sel_hi:[1,0]
	v_pk_mul_f32 v[46:47], v[46:47], v[128:129] op_sel_hi:[1,0]
; template <int CGM>
; __device__ __forceinline__ void step_int(const bf16x8 (&kf)[4][2], const bf16x8 (&q)[2][2], float farb, const bool (&selq)[2],
;                                          float (&m)[2], float (&l)[2], f32x4 (&o)[2][4], const unsigned char* Vs, int r, int fq) {
;     f32x4 s[2][4]; float mx[2] = {-1e30f, -1e30f};
; #pragma unroll
;     for (int cg_ = 0; cg_ < 2; ++cg_) if ((CGM >> cg_) & 1) { qk(s[cg_], kf, q[cg_], selq[cg_] ? farb - m[cg_] : -1e30f); mx[cg_] = red_max4(max16v(s[cg_])); }
;     if (__any(mx[0] > 0.f || mx[1] > 0.f)) {
; #pragma unroll
;         for (int cg_ = 0; cg_ < 2; ++cg_) if ((CGM >> cg_) & 1) {
;             const float d = fmaxf(mx[cg_], 0.f), sc = __builtin_amdgcn_exp2f(-d); m[cg_] += d; l[cg_] *= sc;
; #pragma unroll
;             for (int df = 0; df < 4; ++df) o[cg_][df] *= sc;
; #pragma unroll
;             for (int f = 0; f < 4; ++f) s[cg_][f] -= d;
;         }
;     }
;     float p[2][4][4];
; #pragma unroll
;     for (int cg_ = 0; cg_ < 2; ++cg_) if ((CGM >> cg_) & 1) {
;         float rs = 0.f;
; #pragma unroll
;         for (int f = 0; f < 4; ++f)
; #pragma unroll
;             for (int i = 0; i < 4; ++i) { const float pe = __builtin_amdgcn_exp2f(s[cg_][f][i]); p[cg_][f][i] = pe; rs += pe; }
;         l[cg_] += rs;
;     }
;     pv2<CGM>(o, p, Vs, r, fq);
; }
.Lsel_c1_exp:
	v_exp_f32_e32 v92, v92
	v_exp_f32_e32 v93, v93
	v_exp_f32_e32 v94, v94
	v_exp_f32_e32 v95, v95
	v_exp_f32_e32 v96, v96
	v_exp_f32_e32 v97, v97
	v_exp_f32_e32 v98, v98
	v_exp_f32_e32 v99, v99
	v_exp_f32_e32 v100, v100
	v_exp_f32_e32 v101, v101
	v_exp_f32_e32 v102, v102
	v_exp_f32_e32 v103, v103
	v_exp_f32_e32 v104, v104
	v_exp_f32_e32 v105, v105
	v_exp_f32_e32 v106, v106
	v_exp_f32_e32 v107, v107
	v_pk_add_f32 v[130:131], v[92:93], v[94:95]
	v_pk_add_f32 v[130:131], v[130:131], v[96:97]
	v_pk_add_f32 v[130:131], v[130:131], v[98:99]
	v_pk_add_f32 v[130:131], v[130:131], v[100:101]
	v_pk_add_f32 v[130:131], v[130:131], v[102:103]
	v_pk_add_f32 v[130:131], v[130:131], v[104:105]
	v_pk_add_f32 v[130:131], v[130:131], v[106:107]
	v_add_f32_e32 v130, v130, v131
	v_add_f32_e32 v127, v127, v130
	v_cvt_pk_bf16_f32 v92, v92, v93
	v_cvt_pk_bf16_f32 v93, v94, v95
	v_cvt_pk_bf16_f32 v94, v96, v97
	v_cvt_pk_bf16_f32 v95, v98, v99
	v_cvt_pk_bf16_f32 v96, v100, v101
	v_cvt_pk_bf16_f32 v97, v102, v103
	v_cvt_pk_bf16_f32 v98, v104, v105
	v_cvt_pk_bf16_f32 v99, v106, v107
	s_waitcnt lgkmcnt(0)
	s_nop 0
	v_mfma_f32_16x16x32_bf16 v[56:59], v[88:91], v[92:95], v[56:59]
	v_mfma_f32_16x16x32_bf16 v[52:55], v[80:83], v[92:95], v[52:55]
	v_mfma_f32_16x16x32_bf16 v[48:51], v[72:75], v[92:95], v[48:51]
	v_mfma_f32_16x16x32_bf16 v[44:47], v[60:63], v[92:95], v[44:47]
	v_mfma_f32_16x16x32_bf16 v[56:59], v[84:87], v[96:99], v[56:59]
	v_mfma_f32_16x16x32_bf16 v[52:55], v[76:79], v[96:99], v[52:55]
	v_mfma_f32_16x16x32_bf16 v[48:51], v[68:71], v[96:99], v[48:51]
	v_mfma_f32_16x16x32_bf16 v[44:47], v[64:67], v[96:99], v[44:47]
	s_branch .LBB0_2481
.Lsel_c2:
	v_sub_f32_e32 v144, v18, v125
	v_cndmask_b32_e64 v144, v148, v144, s[8:9]
	v_mov_b32_e32 v145, v144
	v_mov_b64_e32 v[146:147], v[144:145]
	s_nop 0
	s_waitcnt lgkmcnt(7)
	v_mfma_f32_16x16x32_bf16 v[108:111], v[88:91], v[10:13], v[144:147]
	s_waitcnt lgkmcnt(6)
	v_mfma_f32_16x16x32_bf16 v[112:115], v[80:83], v[10:13], v[144:147]
	s_waitcnt lgkmcnt(5)
	v_mfma_f32_16x16x32_bf16 v[108:111], v[84:87], v[14:17], v[108:111]
	s_waitcnt lgkmcnt(4)
	v_mfma_f32_16x16x32_bf16 v[112:115], v[76:79], v[14:17], v[112:115]
	s_waitcnt lgkmcnt(3)
	v_mfma_f32_16x16x32_bf16 v[116:119], v[72:75], v[10:13], v[144:147]
	s_waitcnt lgkmcnt(2)
	v_mfma_f32_16x16x32_bf16 v[120:123], v[60:63], v[10:13], v[144:147]
	s_waitcnt lgkmcnt(1)
	v_mfma_f32_16x16x32_bf16 v[116:119], v[68:71], v[14:17], v[116:119]
	s_waitcnt lgkmcnt(0)
	v_mfma_f32_16x16x32_bf16 v[120:123], v[64:67], v[14:17], v[120:123]
	ds_read_b128 v[88:91], v143 offset:8192
	ds_read_b128 v[80:83], v143 offset:8704
	ds_read_b128 v[72:75], v143 offset:12288
	ds_read_b128 v[60:63], v143 offset:12800
	v_max3_f32 v144, v108, v109, v110
	v_max3_f32 v145, v111, v112, v113
	v_max3_f32 v146, v114, v115, v116
	v_max3_f32 v147, v117, v118, v119
	v_max3_f32 v144, v144, v120, v121
	v_max3_f32 v145, v145, v122, v123
	v_max3_f32 v144, v144, v145, v146
	v_max_f32_e32 v144, v144, v147
	v_mov_b32_e32 v145, v144
	ds_read_b128 v[84:87], v142 offset:8192
	ds_read_b128 v[76:79], v142 offset:8704
	v_permlane16_swap_b32_e32 v144, v145
	v_max_f32_e32 v144, v144, v145
	v_mov_b32_e32 v145, v144
	ds_read_b128 v[68:71], v142 offset:12288
	ds_read_b128 v[64:67], v142 offset:12800
	v_permlane32_swap_b32_e32 v144, v145
	v_max_f32_e32 v144, v144, v145
	v_cmp_lt_f32_e32 vcc, 0, v144
	s_cbranch_vccz .Lsel_c2_exp
	v_max_f32_e32 v147, 0, v144
	v_exp_f32_e64 v146, -v147
	v_add_f32_e32 v125, v125, v147
	v_sub_f32_e32 v108, v108, v147
	v_sub_f32_e32 v109, v109, v147
	v_sub_f32_e32 v110, v110, v147
	v_sub_f32_e32 v111, v111, v147
	v_sub_f32_e32 v112, v112, v147
	v_sub_f32_e32 v113, v113, v147
	v_sub_f32_e32 v114, v114, v147
	v_sub_f32_e32 v115, v115, v147
	v_sub_f32_e32 v116, v116, v147
	v_sub_f32_e32 v117, v117, v147
	v_sub_f32_e32 v118, v118, v147
	v_sub_f32_e32 v119, v119, v147
	v_sub_f32_e32 v120, v120, v147
	v_sub_f32_e32 v121, v121, v147
	v_sub_f32_e32 v122, v122, v147
	v_sub_f32_e32 v123, v123, v147
	v_mul_f32_e32 v126, v126, v146
	v_pk_mul_f32 v[40:41], v[40:41], v[146:147] op_sel_hi:[1,0]
	v_pk_mul_f32 v[42:43], v[42:43], v[146:147] op_sel_hi:[1,0]
	v_pk_mul_f32 v[28:29], v[28:29], v[146:147] op_sel_hi:[1,0]
	v_pk_mul_f32 v[30:31], v[30:31], v[146:147] op_sel_hi:[1,0]
	v_pk_mul_f32 v[24:25], v[24:25], v[146:147] op_sel_hi:[1,0]
	v_pk_mul_f32 v[26:27], v[26:27], v[146:147] op_sel_hi:[1,0]
	v_pk_mul_f32 v[20:21], v[20:21], v[146:147] op_sel_hi:[1,0]
	v_pk_mul_f32 v[22:23], v[22:23], v[146:147] op_sel_hi:[1,0]
.Lsel_c2_exp:
	v_exp_f32_e32 v108, v108
	v_exp_f32_e32 v109, v109
	v_exp_f32_e32 v110, v110
	v_exp_f32_e32 v111, v111
	v_exp_f32_e32 v112, v112
	v_exp_f32_e32 v113, v113
	v_exp_f32_e32 v114, v114
	v_exp_f32_e32 v115, v115
	v_exp_f32_e32 v116, v116
	v_exp_f32_e32 v117, v117
	v_exp_f32_e32 v118, v118
	v_exp_f32_e32 v119, v119
	v_exp_f32_e32 v120, v120
	v_exp_f32_e32 v121, v121
	v_exp_f32_e32 v122, v122
	v_exp_f32_e32 v123, v123
	v_pk_add_f32 v[146:147], v[108:109], v[110:111]
	v_pk_add_f32 v[146:147], v[146:147], v[112:113]
	v_pk_add_f32 v[146:147], v[146:147], v[114:115]
	v_pk_add_f32 v[146:147], v[146:147], v[116:117]
	v_pk_add_f32 v[146:147], v[146:147], v[118:119]
	v_pk_add_f32 v[146:147], v[146:147], v[120:121]
	v_pk_add_f32 v[146:147], v[146:147], v[122:123]
	v_add_f32_e32 v146, v146, v147
	v_add_f32_e32 v126, v126, v146
	v_cvt_pk_bf16_f32 v108, v108, v109
	v_cvt_pk_bf16_f32 v109, v110, v111
	v_cvt_pk_bf16_f32 v110, v112, v113
	v_cvt_pk_bf16_f32 v111, v114, v115
	v_cvt_pk_bf16_f32 v112, v116, v117
	v_cvt_pk_bf16_f32 v113, v118, v119
	v_cvt_pk_bf16_f32 v114, v120, v121
	v_cvt_pk_bf16_f32 v115, v122, v123
	s_waitcnt lgkmcnt(0)
	s_nop 0
	v_mfma_f32_16x16x32_bf16 v[40:43], v[88:91], v[108:111], v[40:43]
	v_mfma_f32_16x16x32_bf16 v[28:31], v[80:83], v[108:111], v[28:31]
	v_mfma_f32_16x16x32_bf16 v[24:27], v[72:75], v[108:111], v[24:27]
	v_mfma_f32_16x16x32_bf16 v[20:23], v[60:63], v[108:111], v[20:23]
	v_mfma_f32_16x16x32_bf16 v[40:43], v[84:87], v[112:115], v[40:43]
	v_mfma_f32_16x16x32_bf16 v[28:31], v[76:79], v[112:115], v[28:31]
	v_mfma_f32_16x16x32_bf16 v[24:27], v[68:71], v[112:115], v[24:27]
	v_mfma_f32_16x16x32_bf16 v[20:23], v[64:67], v[112:115], v[20:23]
	s_branch .LBB0_2481

; template <int CGM>
; __device__ __forceinline__ void step_int(const bf16x8 (&kf)[4][2], const bf16x8 (&q)[2][2], float farb, const bool (&selq)[2],
;                                          float (&m)[2], float (&l)[2], f32x4 (&o)[2][4], const unsigned char* Vs, int r, int fq) {
;     f32x4 s[2][4]; float mx[2] = {-1e30f, -1e30f};
; #pragma unroll
;     for (int cg_ = 0; cg_ < 2; ++cg_) if ((CGM >> cg_) & 1) { qk(s[cg_], kf, q[cg_], selq[cg_] ? farb - m[cg_] : -1e30f); mx[cg_] = red_max4(max16v(s[cg_])); }
;     if (__any(mx[0] > 0.f || mx[1] > 0.f)) {
; #pragma unroll
;         for (int cg_ = 0; cg_ < 2; ++cg_) if ((CGM >> cg_) & 1) {
;             const float d = fmaxf(mx[cg_], 0.f), sc = __builtin_amdgcn_exp2f(-d); m[cg_] += d; l[cg_] *= sc;
; #pragma unroll
;             for (int df = 0; df < 4; ++df) o[cg_][df] *= sc;
; #pragma unroll
;             for (int f = 0; f < 4; ++f) s[cg_][f] -= d;
;         }
;     }
.Lwin_int:
	v_sub_f32_e32 v188, v18, v156
	v_sub_f32_e32 v192, v18, v157
	v_mov_b32_e32 v189, v188
	v_mov_b32_e32 v193, v192
	v_mov_b64_e32 v[190:191], v[188:189]
	v_mov_b64_e32 v[194:195], v[192:193]
	s_waitcnt lgkmcnt(7)
	v_mfma_f32_16x16x32_bf16 v[116:119], v[80:83], v[2:5], v[188:191]
	v_mfma_f32_16x16x32_bf16 v[136:139], v[80:83], v[10:13], v[192:195]
	s_waitcnt lgkmcnt(6)
	v_mfma_f32_16x16x32_bf16 v[120:123], v[72:75], v[2:5], v[188:191]
	v_mfma_f32_16x16x32_bf16 v[140:143], v[72:75], v[10:13], v[192:195]
	s_waitcnt lgkmcnt(5)
	v_mfma_f32_16x16x32_bf16 v[116:119], v[76:79], v[6:9], v[116:119]
	v_mfma_f32_16x16x32_bf16 v[136:139], v[76:79], v[14:17], v[136:139]
	s_waitcnt lgkmcnt(4)
	v_mfma_f32_16x16x32_bf16 v[120:123], v[68:71], v[6:9], v[120:123]
	v_mfma_f32_16x16x32_bf16 v[140:143], v[68:71], v[14:17], v[140:143]
	s_waitcnt lgkmcnt(3)
	v_mfma_f32_16x16x32_bf16 v[124:127], v[60:63], v[2:5], v[188:191]
	v_mfma_f32_16x16x32_bf16 v[144:147], v[60:63], v[10:13], v[192:195]
	s_waitcnt lgkmcnt(2)
	v_mfma_f32_16x16x32_bf16 v[132:135], v[56:59], v[2:5], v[188:191]
	v_mfma_f32_16x16x32_bf16 v[184:187], v[56:59], v[10:13], v[192:195]
	s_waitcnt lgkmcnt(1)
	v_mfma_f32_16x16x32_bf16 v[124:127], v[64:67], v[6:9], v[124:127]
	v_mfma_f32_16x16x32_bf16 v[144:147], v[64:67], v[14:17], v[144:147]
	s_waitcnt lgkmcnt(0)
	v_mfma_f32_16x16x32_bf16 v[132:135], v[52:55], v[6:9], v[132:135]
	v_mfma_f32_16x16x32_bf16 v[184:187], v[52:55], v[14:17], v[184:187]
	ds_read_b128 v[80:83], v149 offset:8192
	ds_read_b128 v[72:75], v149 offset:8704
	ds_read_b128 v[60:63], v149 offset:12288
	ds_read_b128 v[56:59], v149 offset:12800
	v_max3_f32 v188, v116, v117, v118
	v_max3_f32 v189, v119, v120, v121
	v_max3_f32 v192, v136, v137, v138
	v_max3_f32 v193, v139, v140, v141
	v_max3_f32 v190, v122, v123, v124
	v_max3_f32 v191, v125, v126, v127
	v_max3_f32 v194, v142, v143, v144
	v_max3_f32 v195, v145, v146, v147
	v_max3_f32 v188, v188, v132, v133
	v_max3_f32 v189, v189, v134, v135
	v_max3_f32 v192, v192, v184, v185
	v_max3_f32 v193, v193, v186, v187
	v_max3_f32 v188, v188, v189, v190
	v_max3_f32 v192, v192, v193, v194
	v_max_f32_e32 v188, v188, v191
	v_max_f32_e32 v192, v192, v195
	v_mov_b32_e32 v189, v188
	v_mov_b32_e32 v193, v192
	ds_read_b128 v[76:79], v182 offset:8192
	ds_read_b128 v[68:71], v182 offset:8704
	v_permlane16_swap_b32_e32 v188, v189
	v_permlane16_swap_b32_e32 v192, v193
	v_max_f32_e32 v188, v188, v189
	v_max_f32_e32 v192, v192, v193
	v_mov_b32_e32 v189, v188
	v_mov_b32_e32 v193, v192
	ds_read_b128 v[64:67], v182 offset:12288
	ds_read_b128 v[52:55], v182 offset:12800
	v_permlane32_swap_b32_e32 v188, v189
	v_permlane32_swap_b32_e32 v192, v193
	v_max_f32_e32 v188, v188, v189
	v_max_f32_e32 v192, v192, v193
	v_max_f32_e32 v189, v188, v192
	v_cmp_lt_f32_e32 vcc, 0, v189
	s_cbranch_vccz .Lwin_int_exp
	v_max_f32_e32 v190, 0, v188
	v_max_f32_e32 v195, 0, v192
	v_exp_f32_e64 v188, -v190
	v_exp_f32_e64 v194, -v195
	v_add_f32_e32 v156, v156, v190
	v_add_f32_e32 v157, v157, v195
	v_sub_f32_e32 v116, v116, v190
	v_sub_f32_e32 v117, v117, v190
	v_sub_f32_e32 v118, v118, v190
	v_sub_f32_e32 v119, v119, v190
	v_sub_f32_e32 v120, v120, v190
	v_sub_f32_e32 v121, v121, v190
	v_sub_f32_e32 v122, v122, v190
	v_sub_f32_e32 v123, v123, v190
	v_sub_f32_e32 v124, v124, v190
	v_sub_f32_e32 v125, v125, v190
	v_sub_f32_e32 v126, v126, v190
	v_sub_f32_e32 v127, v127, v190
	v_sub_f32_e32 v132, v132, v190
	v_sub_f32_e32 v133, v133, v190
	v_sub_f32_e32 v134, v134, v190
	v_sub_f32_e32 v135, v135, v190
	v_sub_f32_e32 v136, v136, v195
	v_sub_f32_e32 v137, v137, v195
	v_sub_f32_e32 v138, v138, v195
	v_sub_f32_e32 v139, v139, v195
	v_sub_f32_e32 v140, v140, v195
	v_sub_f32_e32 v141, v141, v195
	v_sub_f32_e32 v142, v142, v195
	v_sub_f32_e32 v143, v143, v195
	v_sub_f32_e32 v144, v144, v195
	v_sub_f32_e32 v145, v145, v195
	v_sub_f32_e32 v146, v146, v195
	v_sub_f32_e32 v147, v147, v195
	v_sub_f32_e32 v184, v184, v195
	v_sub_f32_e32 v185, v185, v195
	v_sub_f32_e32 v186, v186, v195
	v_sub_f32_e32 v187, v187, v195
	v_mul_f32_e32 v155, v155, v188
	v_pk_mul_f32 v[48:49], v[48:49], v[188:189] op_sel_hi:[1,0]
	v_pk_mul_f32 v[50:51], v[50:51], v[188:189] op_sel_hi:[1,0]
	v_pk_mul_f32 v[40:41], v[40:41], v[188:189] op_sel_hi:[1,0]
	v_pk_mul_f32 v[42:43], v[42:43], v[188:189] op_sel_hi:[1,0]
	v_pk_mul_f32 v[32:33], v[32:33], v[188:189] op_sel_hi:[1,0]
	v_pk_mul_f32 v[34:35], v[34:35], v[188:189] op_sel_hi:[1,0]
	v_pk_mul_f32 v[24:25], v[24:25], v[188:189] op_sel_hi:[1,0]
	v_pk_mul_f32 v[26:27], v[26:27], v[188:189] op_sel_hi:[1,0]
	v_mul_f32_e32 v154, v154, v194
	v_pk_mul_f32 v[44:45], v[44:45], v[194:195] op_sel_hi:[1,0]
	v_pk_mul_f32 v[46:47], v[46:47], v[194:195] op_sel_hi:[1,0]
	v_pk_mul_f32 v[36:37], v[36:37], v[194:195] op_sel_hi:[1,0]
	v_pk_mul_f32 v[38:39], v[38:39], v[194:195] op_sel_hi:[1,0]
	v_pk_mul_f32 v[28:29], v[28:29], v[194:195] op_sel_hi:[1,0]
	v_pk_mul_f32 v[30:31], v[30:31], v[194:195] op_sel_hi:[1,0]
	v_pk_mul_f32 v[20:21], v[20:21], v[194:195] op_sel_hi:[1,0]
	v_pk_mul_f32 v[22:23], v[22:23], v[194:195] op_sel_hi:[1,0]
; template <int CGM>
; __device__ __forceinline__ void step_int(const bf16x8 (&kf)[4][2], const bf16x8 (&q)[2][2], float farb, const bool (&selq)[2],
;                                          float (&m)[2], float (&l)[2], f32x4 (&o)[2][4], const unsigned char* Vs, int r, int fq) {
;     ...
;     float p[2][4][4];
; #pragma unroll
;     for (int cg_ = 0; cg_ < 2; ++cg_) if ((CGM >> cg_) & 1) {
;         float rs = 0.f;
; #pragma unroll
;         for (int f = 0; f < 4; ++f)
; #pragma unroll
;             for (int i = 0; i < 4; ++i) { const float pe = __builtin_amdgcn_exp2f(s[cg_][f][i]); p[cg_][f][i] = pe; rs += pe; }
;         l[cg_] += rs;
;     }
;     pv2<CGM>(o, p, Vs, r, fq);
; }
.Lwin_int_exp:
	v_exp_f32_e32 v116, v116
	v_exp_f32_e32 v117, v117
	v_exp_f32_e32 v118, v118
	v_exp_f32_e32 v119, v119
	v_exp_f32_e32 v120, v120
	v_exp_f32_e32 v121, v121
	v_exp_f32_e32 v122, v122
	v_exp_f32_e32 v123, v123
	v_exp_f32_e32 v124, v124
	v_exp_f32_e32 v125, v125
	v_exp_f32_e32 v126, v126
	v_exp_f32_e32 v127, v127
	v_exp_f32_e32 v132, v132
	v_exp_f32_e32 v133, v133
	v_exp_f32_e32 v134, v134
	v_exp_f32_e32 v135, v135
	v_exp_f32_e32 v136, v136
	v_exp_f32_e32 v137, v137
	v_exp_f32_e32 v138, v138
	v_exp_f32_e32 v139, v139
	v_exp_f32_e32 v140, v140
	v_exp_f32_e32 v141, v141
	v_exp_f32_e32 v142, v142
	v_exp_f32_e32 v143, v143
	v_exp_f32_e32 v144, v144
	v_exp_f32_e32 v145, v145
	v_exp_f32_e32 v146, v146
	v_exp_f32_e32 v147, v147
	v_exp_f32_e32 v184, v184
	v_exp_f32_e32 v185, v185
	v_exp_f32_e32 v186, v186
	v_exp_f32_e32 v187, v187
	v_pk_add_f32 v[190:191], v[116:117], v[118:119]
	v_pk_add_f32 v[190:191], v[190:191], v[120:121]
	v_pk_add_f32 v[190:191], v[190:191], v[122:123]
	v_pk_add_f32 v[190:191], v[190:191], v[124:125]
	v_pk_add_f32 v[190:191], v[190:191], v[126:127]
	v_pk_add_f32 v[190:191], v[190:191], v[132:133]
	v_pk_add_f32 v[190:191], v[190:191], v[134:135]
	v_pk_add_f32 v[194:195], v[136:137], v[138:139]
	v_pk_add_f32 v[194:195], v[194:195], v[140:141]
	v_pk_add_f32 v[194:195], v[194:195], v[142:143]
	v_pk_add_f32 v[194:195], v[194:195], v[144:145]
	v_pk_add_f32 v[194:195], v[194:195], v[146:147]
	v_pk_add_f32 v[194:195], v[194:195], v[184:185]
	v_pk_add_f32 v[194:195], v[194:195], v[186:187]
	v_add_f32_e32 v190, v190, v191
	v_add_f32_e32 v194, v194, v195
	v_add_f32_e32 v129, v155, v190
	v_add_f32_e32 v128, v154, v194
	v_cvt_pk_bf16_f32 v116, v116, v117
	v_cvt_pk_bf16_f32 v117, v118, v119
	v_cvt_pk_bf16_f32 v118, v120, v121
	v_cvt_pk_bf16_f32 v119, v122, v123
	v_cvt_pk_bf16_f32 v120, v124, v125
	v_cvt_pk_bf16_f32 v121, v126, v127
	v_cvt_pk_bf16_f32 v122, v132, v133
	v_cvt_pk_bf16_f32 v123, v134, v135
	v_cvt_pk_bf16_f32 v136, v136, v137
	v_cvt_pk_bf16_f32 v137, v138, v139
	v_cvt_pk_bf16_f32 v138, v140, v141
	v_cvt_pk_bf16_f32 v139, v142, v143
	v_cvt_pk_bf16_f32 v140, v144, v145
	v_cvt_pk_bf16_f32 v141, v146, v147
	v_cvt_pk_bf16_f32 v142, v184, v185
	v_cvt_pk_bf16_f32 v143, v186, v187
	v_mov_b64_e32 v[158:159], v[156:157]
	s_waitcnt lgkmcnt(0)
	v_mfma_f32_16x16x32_bf16 v[48:51], v[80:83], v[116:119], v[48:51]
	v_mfma_f32_16x16x32_bf16 v[44:47], v[80:83], v[136:139], v[44:47]
	v_mfma_f32_16x16x32_bf16 v[40:43], v[72:75], v[116:119], v[40:43]
	v_mfma_f32_16x16x32_bf16 v[36:39], v[72:75], v[136:139], v[36:39]
	v_mfma_f32_16x16x32_bf16 v[32:35], v[60:63], v[116:119], v[32:35]
	v_mfma_f32_16x16x32_bf16 v[28:31], v[60:63], v[136:139], v[28:31]
	v_mfma_f32_16x16x32_bf16 v[24:27], v[56:59], v[116:119], v[24:27]
	v_mfma_f32_16x16x32_bf16 v[20:23], v[56:59], v[136:139], v[20:23]
	v_mfma_f32_16x16x32_bf16 v[92:95], v[76:79], v[120:123], v[48:51]
	v_mfma_f32_16x16x32_bf16 v[84:87], v[76:79], v[140:143], v[44:47]
	v_mfma_f32_16x16x32_bf16 v[104:107], v[68:71], v[120:123], v[40:43]
	v_mfma_f32_16x16x32_bf16 v[96:99], v[68:71], v[140:143], v[36:39]
	v_mfma_f32_16x16x32_bf16 v[100:103], v[64:67], v[120:123], v[32:35]
	v_mfma_f32_16x16x32_bf16 v[88:91], v[64:67], v[140:143], v[28:31]
	v_mfma_f32_16x16x32_bf16 v[112:115], v[52:55], v[120:123], v[24:27]
	v_mfma_f32_16x16x32_bf16 v[108:111], v[52:55], v[140:143], v[20:23]
	s_branch .LBB0_2733
